# SGU phase: gamma/beta loads batched, prefetch+gu loads flat->global (no longer on lgkmcnt), MFMA blocks read all LDS fragments up front with counted waits
# baseline (speedup 1.0000x reference)
; #define LAS __attribute__((address_space(3)))
; __device__ __forceinline__ float bf_lo(unsigned w) { return __uint_as_float(w << 16); }
; __device__ __forceinline__ float bf_hi(unsigned w) { return __uint_as_float(w & 0xffff0000u); }
; __device__ __forceinline__ bf16_t f2bf(float f) { return (bf16_t)(cvt_pk_bf16(f, 0.f) & 0xffffu); }
; __device__ __forceinline__ void sgu_phase(const bf16_t* gu, const bf16_t* gv, const float* __restrict__ statsv, const float* __restrict__ lng, const float* __restrict__ lnb, const float* __restrict__ wsp, const float* __restrict__ bs, ...
;     ...
;         {
;             const int s = tid & 127; const float mean = st[2 * s], rstd = st[2 * s + 1];
; #pragma unroll
;             for (int i = 0; i < 4; ++i) {
;                 const int c8 = (tid >> 7) + 4 * i, col = g * 128 + c8 * 8;
;                 const u32x4 w = gvw[i];
;                 const f32x4 g0 = *(const f32x4*)(lng + col), g1 = *(const f32x4*)(lng + col + 4), b0 = *(const f32x4*)(lnb + col), b1 = *(const f32x4*)(lnb + col + 4);
;                 LAS bf16_t* vp = (LAS bf16_t*)(vT + (c8 * 8) * P) + s;
;                 vp[0 * (P / 2)] = f2bf((bf_lo(w.x) - mean) * rstd * g0[0] + b0[0]); vp[1 * (P / 2)] = f2bf((bf_hi(w.x) - mean) * rstd * g0[1] + b0[1]);
;                 vp[2 * (P / 2)] = f2bf((bf_lo(w.y) - mean) * rstd * g0[2] + b0[2]); vp[3 * (P / 2)] = f2bf((bf_hi(w.y) - mean) * rstd * g0[3] + b0[3]);
;                 vp[4 * (P / 2)] = f2bf((bf_lo(w.z) - mean) * rstd * g1[0] + b1[0]); vp[5 * (P / 2)] = f2bf((bf_hi(w.z) - mean) * rstd * g1[1] + b1[1]);
;                 vp[6 * (P / 2)] = f2bf((bf_lo(w.w) - mean) * rstd * g1[2] + b1[2]); vp[7 * (P / 2)] = f2bf((bf_hi(w.w) - mean) * rstd * g1[3] + b1[3]);
;             }
.LBB0_480:
	s_or_b64 exec, exec, s[76:77]
	s_and_b32 s79, s73, 0x380
	v_add_u32_e32 v58, s79, v94
	s_waitcnt lgkmcnt(1)
	v_ashrrev_i32_e32 v59, 31, v58
	v_lshlrev_b64 v[58:59], 2, v[58:59]
	v_lshl_add_u64 v[70:71], s[92:93], 0, v[58:59]
	v_lshl_add_u64 v[68:69], s[94:95], 0, v[58:59]
	s_waitcnt lgkmcnt(0)
	s_barrier
	ds_read_b64 v[66:67], v124
	global_load_dwordx4 v[62:65], v[70:71], off offset:16
	global_load_dwordx4 v[72:75], v[70:71], off
	global_load_dwordx4 v[58:61], v[68:69], off offset:16
	global_load_dwordx4 v[76:79], v[68:69], off
	global_load_dwordx4 v[142:145], v[70:71], off offset:144
	global_load_dwordx4 v[146:149], v[70:71], off offset:128
	global_load_dwordx4 v[150:153], v[68:69], off offset:144
	global_load_dwordx4 v[154:157], v[68:69], off offset:128
	global_load_dwordx4 v[158:161], v[70:71], off offset:272
	global_load_dwordx4 v[162:165], v[70:71], off offset:256
	global_load_dwordx4 v[166:169], v[68:69], off offset:272
	global_load_dwordx4 v[172:175], v[68:69], off offset:256
	global_load_dwordx4 v[176:179], v[70:71], off offset:400
	global_load_dwordx4 v[180:183], v[70:71], off offset:384
	global_load_dwordx4 v[184:187], v[68:69], off offset:400
	global_load_dwordx4 v[188:191], v[68:69], off offset:384
	v_lshlrev_b32_e32 v80, 16, v10
	v_readlane_b32 s76, v251, 8
	s_waitcnt lgkmcnt(0)
	v_sub_f32_e32 v80, v80, v66
	v_mul_f32_e32 v80, v67, v80
	s_add_i32 s78, s78, s76
	v_readlane_b32 s77, v251, 9
	s_cmpk_gt_i32 s78, 0x3ff
	s_cselect_b64 s[76:77], -1, 0
	s_and_b64 vcc, exec, s[76:77]
	s_waitcnt vmcnt(0)
	v_fma_f32 v72, v80, v72, v76
	v_cvt_pk_bf16_f32 v72, v72, v1
	ds_write_b16 v129, v72 offset:1024
	v_and_b32_e32 v72, 0xffff0000, v10
	v_sub_f32_e32 v72, v72, v66
	v_mul_f32_e32 v72, v67, v72
	v_fma_f32 v72, v72, v73, v77
	v_cvt_pk_bf16_f32 v72, v72, v1
	ds_write_b16 v129, v72 offset:1296
	v_lshlrev_b32_e32 v72, 16, v11
	v_sub_f32_e32 v72, v72, v66
	v_mul_f32_e32 v72, v67, v72
	v_fma_f32 v72, v72, v74, v78
	v_cvt_pk_bf16_f32 v72, v72, v1
	ds_write_b16 v129, v72 offset:1568
	v_and_b32_e32 v72, 0xffff0000, v11
	v_sub_f32_e32 v72, v72, v66
	v_mul_f32_e32 v72, v67, v72
	v_fmac_f32_e32 v79, v72, v75
	v_cvt_pk_bf16_f32 v72, v79, v1
	ds_write_b16 v129, v72 offset:1840
	v_lshlrev_b32_e32 v72, 16, v12
	v_sub_f32_e32 v72, v72, v66
	v_mul_f32_e32 v72, v67, v72
	v_fma_f32 v58, v72, v62, v58
	v_cvt_pk_bf16_f32 v58, v58, v1
	ds_write_b16 v129, v58 offset:2112
	v_and_b32_e32 v58, 0xffff0000, v12
	v_sub_f32_e32 v58, v58, v66
	v_mul_f32_e32 v58, v67, v58
	v_fma_f32 v58, v58, v63, v59
	v_cvt_pk_bf16_f32 v58, v58, v1
	ds_write_b16 v129, v58 offset:2384
	v_lshlrev_b32_e32 v58, 16, v13
	v_sub_f32_e32 v58, v58, v66
	v_mul_f32_e32 v58, v67, v58
	v_fma_f32 v58, v58, v64, v60
	v_cvt_pk_bf16_f32 v58, v58, v1
	ds_write_b16 v129, v58 offset:2656
	v_and_b32_e32 v58, 0xffff0000, v13
	v_sub_f32_e32 v58, v58, v66
	v_mul_f32_e32 v58, v67, v58
	v_fmac_f32_e32 v61, v58, v65
	v_cvt_pk_bf16_f32 v58, v61, v1
	ds_write_b16 v129, v58 offset:2928
	v_lshlrev_b32_e32 v80, 16, v14
	v_sub_f32_e32 v80, v80, v66
	v_mul_f32_e32 v80, v67, v80
	s_waitcnt vmcnt(0)
	v_fma_f32 v146, v80, v146, v154
	v_cvt_pk_bf16_f32 v146, v146, v1
	ds_write_b16 v129, v146 offset:9728
	v_and_b32_e32 v146, 0xffff0000, v14
	v_sub_f32_e32 v146, v146, v66
	v_mul_f32_e32 v146, v67, v146
	v_fma_f32 v146, v146, v147, v155
	v_cvt_pk_bf16_f32 v146, v146, v1
	ds_write_b16 v129, v146 offset:10000
	v_lshlrev_b32_e32 v146, 16, v15
	v_sub_f32_e32 v146, v146, v66
	v_mul_f32_e32 v146, v67, v146
	v_fma_f32 v146, v146, v148, v156
	v_cvt_pk_bf16_f32 v146, v146, v1
	ds_write_b16 v129, v146 offset:10272
	v_and_b32_e32 v146, 0xffff0000, v15
	v_sub_f32_e32 v146, v146, v66
	v_mul_f32_e32 v146, v67, v146
	v_fmac_f32_e32 v157, v146, v149
	v_cvt_pk_bf16_f32 v146, v157, v1
	ds_write_b16 v129, v146 offset:10544
	v_lshlrev_b32_e32 v146, 16, v16
	v_sub_f32_e32 v146, v146, v66
	v_mul_f32_e32 v146, v67, v146
	v_fma_f32 v150, v146, v142, v150
	v_cvt_pk_bf16_f32 v150, v150, v1
	ds_write_b16 v129, v150 offset:10816
	v_and_b32_e32 v150, 0xffff0000, v16
	v_sub_f32_e32 v150, v150, v66
	v_mul_f32_e32 v150, v67, v150
	v_fma_f32 v150, v150, v143, v151
	v_cvt_pk_bf16_f32 v150, v150, v1
	ds_write_b16 v129, v150 offset:11088
	v_lshlrev_b32_e32 v150, 16, v17
	v_sub_f32_e32 v150, v150, v66
	v_mul_f32_e32 v150, v67, v150
	v_fma_f32 v150, v150, v144, v152
	v_cvt_pk_bf16_f32 v150, v150, v1
	ds_write_b16 v129, v150 offset:11360
	v_and_b32_e32 v150, 0xffff0000, v17
	v_sub_f32_e32 v150, v150, v66
	v_mul_f32_e32 v150, v67, v150
	v_fmac_f32_e32 v153, v150, v145
	v_cvt_pk_bf16_f32 v150, v153, v1
	ds_write_b16 v129, v150 offset:11632
	v_lshlrev_b32_e32 v80, 16, v18
	v_sub_f32_e32 v80, v80, v66
	v_mul_f32_e32 v80, v67, v80
	s_waitcnt vmcnt(0)
	v_fma_f32 v162, v80, v162, v172
	v_cvt_pk_bf16_f32 v162, v162, v1
	ds_write_b16 v129, v162 offset:18432
	v_and_b32_e32 v162, 0xffff0000, v18
	v_sub_f32_e32 v162, v162, v66
	v_mul_f32_e32 v162, v67, v162
	v_fma_f32 v162, v162, v163, v173
	v_cvt_pk_bf16_f32 v162, v162, v1
	ds_write_b16 v129, v162 offset:18704
	v_lshlrev_b32_e32 v162, 16, v19
	v_sub_f32_e32 v162, v162, v66
	v_mul_f32_e32 v162, v67, v162
	v_fma_f32 v162, v162, v164, v174
	v_cvt_pk_bf16_f32 v162, v162, v1
	ds_write_b16 v129, v162 offset:18976
	v_and_b32_e32 v162, 0xffff0000, v19
	v_sub_f32_e32 v162, v162, v66
	v_mul_f32_e32 v162, v67, v162
	v_fmac_f32_e32 v175, v162, v165
	v_cvt_pk_bf16_f32 v162, v175, v1
	ds_write_b16 v129, v162 offset:19248
	v_lshlrev_b32_e32 v162, 16, v20
	v_sub_f32_e32 v162, v162, v66
	v_mul_f32_e32 v162, v67, v162
	v_fma_f32 v166, v162, v158, v166
	v_cvt_pk_bf16_f32 v166, v166, v1
	ds_write_b16 v129, v166 offset:19520
	v_and_b32_e32 v166, 0xffff0000, v20
	v_sub_f32_e32 v166, v166, v66
	v_mul_f32_e32 v166, v67, v166
	v_fma_f32 v166, v166, v159, v167
	v_cvt_pk_bf16_f32 v166, v166, v1
	ds_write_b16 v129, v166 offset:19792
	v_lshlrev_b32_e32 v166, 16, v21
	v_sub_f32_e32 v166, v166, v66
	v_mul_f32_e32 v166, v67, v166
	v_fma_f32 v166, v166, v160, v168
	v_cvt_pk_bf16_f32 v166, v166, v1
	ds_write_b16 v129, v166 offset:20064
	v_and_b32_e32 v166, 0xffff0000, v21
	v_sub_f32_e32 v166, v166, v66
	v_mul_f32_e32 v166, v67, v166
	v_fmac_f32_e32 v169, v166, v161
	v_cvt_pk_bf16_f32 v166, v169, v1
	ds_write_b16 v129, v166 offset:20336
	s_nop 0
	v_lshlrev_b32_e32 v68, 16, v22
	v_sub_f32_e32 v68, v68, v66
	v_mul_f32_e32 v68, v67, v68
	s_waitcnt vmcnt(0)
; #define LAS __attribute__((address_space(3)))
; __device__ __forceinline__ unsigned cvt_pk_bf16(float lo, float hi) { unsigned r; asm volatile("v_cvt_pk_bf16_f32 %0, %1, %2" : "=v"(r) : "v"(lo), "v"(hi)); return r; }
; __device__ __forceinline__ float bf_lo(unsigned w) { return __uint_as_float(w << 16); }
; __device__ __forceinline__ float bf_hi(unsigned w) { return __uint_as_float(w & 0xffff0000u); }
; __device__ __forceinline__ bf16_t f2bf(float f) { return (bf16_t)(cvt_pk_bf16(f, 0.f) & 0xffffu); }
; __device__ __forceinline__ void sgu_phase(const bf16_t* gu, const bf16_t* gv, const float* __restrict__ statsv, const float* __restrict__ lng, const float* __restrict__ lnb, const float* __restrict__ wsp, const float* __restrict__ bs, ...
;     ...
;                 vp[0 * (P / 2)] = f2bf((bf_lo(w.x) - mean) * rstd * g0[0] + b0[0]); vp[1 * (P / 2)] = f2bf((bf_hi(w.x) - mean) * rstd * g0[1] + b0[1]);
;                 vp[2 * (P / 2)] = f2bf((bf_lo(w.y) - mean) * rstd * g0[2] + b0[2]); vp[3 * (P / 2)] = f2bf((bf_hi(w.y) - mean) * rstd * g0[3] + b0[3]);
;                 vp[4 * (P / 2)] = f2bf((bf_lo(w.z) - mean) * rstd * g1[0] + b1[0]); vp[5 * (P / 2)] = f2bf((bf_hi(w.z) - mean) * rstd * g1[1] + b1[1]);
;                 vp[6 * (P / 2)] = f2bf((bf_lo(w.w) - mean) * rstd * g1[2] + b1[2]); vp[7 * (P / 2)] = f2bf((bf_hi(w.w) - mean) * rstd * g1[3] + b1[3]);
;             }
; #pragma unroll
;             for (int i = 0; i < 8; ++i) {
;                 const int t = (tid >> 5) + 16 * i, s4 = (tid & 31) * 4;
;                 u32x2 pk; pk.x = cvt_pk_bf16(s4 + 0 <= t ? wv[i][0] : 0.f, s4 + 1 <= t ? wv[i][1] : 0.f); pk.y = cvt_pk_bf16(s4 + 2 <= t ? wv[i][2] : 0.f, s4 + 3 <= t ? wv[i][3] : 0.f);
;                 *(LAS u32x2*)(Wl + t * P + s4 * 2) = pk;
;             }
	v_fma_f32 v180, v68, v180, v188
	v_cvt_pk_bf16_f32 v180, v180, v1
	ds_write_b16 v129, v180 offset:27136
	v_and_b32_e32 v180, 0xffff0000, v22
	v_sub_f32_e32 v180, v180, v66
	v_mul_f32_e32 v180, v67, v180
	v_fma_f32 v180, v180, v181, v189
	v_cvt_pk_bf16_f32 v180, v180, v1
	ds_write_b16 v129, v180 offset:27408
	v_lshlrev_b32_e32 v180, 16, v23
	v_sub_f32_e32 v180, v180, v66
	v_mul_f32_e32 v180, v67, v180
	v_fma_f32 v180, v180, v182, v190
	v_cvt_pk_bf16_f32 v180, v180, v1
	ds_write_b16 v129, v180 offset:27680
	v_and_b32_e32 v180, 0xffff0000, v23
	v_sub_f32_e32 v180, v180, v66
	v_mul_f32_e32 v180, v67, v180
	v_fmac_f32_e32 v191, v180, v183
	v_cvt_pk_bf16_f32 v180, v191, v1
	ds_write_b16 v129, v180 offset:27952
	v_lshlrev_b32_e32 v180, 16, v24
	v_sub_f32_e32 v180, v180, v66
	v_mul_f32_e32 v180, v67, v180
	v_fma_f32 v176, v180, v176, v184
	v_cvt_pk_bf16_f32 v176, v176, v1
	ds_write_b16 v129, v176 offset:28224
	v_and_b32_e32 v176, 0xffff0000, v24
	v_sub_f32_e32 v176, v176, v66
	v_mul_f32_e32 v176, v67, v176
	v_fma_f32 v176, v176, v177, v185
	v_cvt_pk_bf16_f32 v176, v176, v1
	ds_write_b16 v129, v176 offset:28496
	v_lshlrev_b32_e32 v176, 16, v25
	v_sub_f32_e32 v176, v176, v66
	v_mul_f32_e32 v176, v67, v176
	v_fma_f32 v176, v176, v178, v186
	v_cvt_pk_bf16_f32 v176, v176, v1
	ds_write_b16 v129, v176 offset:28768
	v_and_b32_e32 v176, 0xffff0000, v25
	v_sub_f32_e32 v176, v176, v66
	v_mul_f32_e32 v176, v67, v176
	v_fmac_f32_e32 v187, v176, v179
	v_cvt_pk_bf16_f32 v176, v187, v1
	ds_write_b16 v129, v176 offset:29040
	v_cndmask_b32_e64 v176, v26, 0, s[68:69]
	v_cndmask_b32_e64 v177, 0, v27, s[4:5]
	v_cvt_pk_bf16_f32 v176, v176, v177
	v_cndmask_b32_e64 v177, v28, 0, s[6:7]
	v_cndmask_b32_e64 v178, v29, 0, s[8:9]
	v_cvt_pk_bf16_f32 v177, v177, v178
	v_add_u32_e32 v178, v125, v127
	ds_write_b64 v178, v[176:177] offset:35840
	v_cndmask_b32_e64 v176, v30, 0, s[10:11]
	v_cndmask_b32_e64 v177, 0, v31, s[12:13]
	v_cvt_pk_bf16_f32 v176, v176, v177
	v_cndmask_b32_e64 v177, v32, 0, s[14:15]
	v_cndmask_b32_e64 v179, v33, 0, s[16:17]
	v_cvt_pk_bf16_f32 v177, v177, v179
	ds_write_b64 v178, v[176:177] offset:40192
	v_cndmask_b32_e64 v176, v34, 0, s[18:19]
	v_cndmask_b32_e64 v177, 0, v35, s[20:21]
	v_cvt_pk_bf16_f32 v176, v176, v177
	v_cndmask_b32_e64 v177, v36, 0, s[22:23]
	v_cndmask_b32_e64 v179, v37, 0, s[24:25]
	v_cvt_pk_bf16_f32 v177, v177, v179
	ds_write_b64 v178, v[176:177] offset:44544
	v_cndmask_b32_e64 v176, v38, 0, s[26:27]
	v_cndmask_b32_e64 v177, 0, v39, s[28:29]
	v_cvt_pk_bf16_f32 v176, v176, v177
	v_cndmask_b32_e64 v177, v40, 0, s[30:31]
	v_cndmask_b32_e64 v179, v41, 0, s[34:35]
	v_cvt_pk_bf16_f32 v177, v177, v179
	ds_write_b64 v178, v[176:177] offset:48896
	v_cndmask_b32_e64 v176, v42, 0, s[36:37]
	v_cndmask_b32_e64 v177, 0, v43, s[38:39]
	v_cvt_pk_bf16_f32 v176, v176, v177
	v_cndmask_b32_e64 v177, v44, 0, s[40:41]
	v_cndmask_b32_e64 v179, v45, 0, s[42:43]
	v_cvt_pk_bf16_f32 v177, v177, v179
	ds_write_b64 v178, v[176:177] offset:53248
	v_cndmask_b32_e64 v176, v46, 0, s[44:45]
	v_cndmask_b32_e64 v177, 0, v47, s[46:47]
	v_cvt_pk_bf16_f32 v176, v176, v177
	v_cndmask_b32_e64 v177, v48, 0, s[48:49]
	v_cndmask_b32_e64 v179, v49, 0, s[50:51]
	v_cvt_pk_bf16_f32 v177, v177, v179
	ds_write_b64 v178, v[176:177] offset:57600
	v_cndmask_b32_e64 v176, v50, 0, s[52:53]
	v_cndmask_b32_e64 v177, 0, v51, s[54:55]
	v_cvt_pk_bf16_f32 v176, v176, v177
	v_cndmask_b32_e64 v177, v52, 0, s[56:57]
	v_cndmask_b32_e64 v179, v53, 0, s[58:59]
	v_cvt_pk_bf16_f32 v177, v177, v179
	ds_write_b64 v178, v[176:177] offset:61952
	v_cndmask_b32_e64 v176, v54, 0, s[60:61]
	v_cndmask_b32_e64 v177, 0, v55, s[62:63]
	v_cvt_pk_bf16_f32 v176, v176, v177
	v_cndmask_b32_e64 v177, v56, 0, s[64:65]
	v_cndmask_b32_e64 v178, v57, 0, s[66:67]
	v_cvt_pk_bf16_f32 v177, v177, v178
	ds_write_b64 v130, v[176:177] offset:61952
	s_waitcnt lgkmcnt(0)
	s_barrier
	s_cbranch_vccnz .LBB0_482
	v_readlane_b32 s2, v250, 54
	s_add_i32 s2, s2, s33
	s_and_b32 s2, s2, 0xffffff80
	v_add_u32_e32 v2, s2, v120
	v_or_b32_e32 v10, s2, v121
	v_readlane_b32 s2, v250, 57
	s_add_i32 s2, s2, s73
	s_and_b32 s2, s2, 0x380
	v_ashrrev_i32_e32 v11, 31, v10
	v_readlane_b32 vcc_lo, v251, 62
	v_lshl_add_u64 v[26:27], s[2:3], 0, v[96:97]
	v_lshlrev_b64 v[10:11], 11, v[10:11]
	v_readlane_b32 vcc_hi, v251, 63
	v_lshlrev_b64 v[26:27], 9, v[26:27]
	v_lshl_add_u64 v[50:51], v[98:99], 0, v[26:27]
	v_lshl_add_u64 v[10:11], vcc, 0, v[10:11]
	s_lshl_b32 vcc_lo, s2, 1
	s_mov_b32 vcc_hi, s3
	s_movk_i32 s2, 0x2000
	v_lshl_add_u64 v[10:11], v[10:11], 0, vcc
	v_add_co_u32_e32 v30, vcc, s2, v50
	s_movk_i32 s2, 0x4000
	s_nop 0
	v_addc_co_u32_e32 v31, vcc, 0, v51, vcc
	v_add_co_u32_e32 v34, vcc, s2, v50
	s_movk_i32 s2, 0x6000
	s_nop 0
	v_addc_co_u32_e32 v35, vcc, 0, v51, vcc
	v_add_co_u32_e32 v38, vcc, s2, v50
	v_ashrrev_i32_e32 v3, 31, v2
	s_nop 0
	v_addc_co_u32_e32 v39, vcc, 0, v51, vcc
	v_add_co_u32_e32 v42, vcc, 0x8000, v50
	v_lshlrev_b64 v[2:3], 7, v[2:3]
	s_nop 0
	v_addc_co_u32_e32 v43, vcc, 0, v51, vcc
	v_add_co_u32_e32 v46, vcc, 0xa000, v50
	v_lshl_add_u64 v[6:7], v[100:101], 0, v[2:3]
	s_nop 0
	v_addc_co_u32_e32 v47, vcc, 0, v51, vcc
	v_add_co_u32_e32 v52, vcc, 0xc000, v50
	v_lshl_add_u64 v[22:23], v[94:95], 1, v[10:11]
	s_nop 0
	v_addc_co_u32_e32 v53, vcc, 0, v51, vcc
	global_load_dwordx4 v[2:5], v[6:7], off
	s_nop 0
	global_load_dwordx4 v[6:9], v[6:7], off offset:16
	s_nop 0
	global_load_dwordx4 v[10:13], v[22:23], off
	global_load_dwordx4 v[14:17], v[22:23], off offset:64
	global_load_dwordx4 v[18:21], v[22:23], off offset:128
	s_nop 0
	global_load_dwordx4 v[22:25], v[22:23], off offset:192
	v_add_co_u32_e32 v54, vcc, 0xe000, v50
	global_load_dwordx4 v[26:29], v[50:51], off
	s_nop 0
	global_load_dwordx4 v[30:33], v[30:31], off
	v_addc_co_u32_e32 v55, vcc, 0, v51, vcc
	global_load_dwordx4 v[34:37], v[34:35], off
	s_nop 0
	global_load_dwordx4 v[38:41], v[38:39], off
	s_nop 0
	global_load_dwordx4 v[42:45], v[42:43], off
	s_nop 0
	global_load_dwordx4 v[46:49], v[46:47], off
	s_nop 0
	global_load_dwordx4 v[50:53], v[52:53], off
	s_nop 0
	global_load_dwordx4 v[54:57], v[54:55], off
; #define LAS __attribute__((address_space(3)))
; #define MFMA16(a, b, c) __builtin_amdgcn_mfma_f32_16x16x32_bf16((a), (b), (c), 0, 0, 0)
; __device__ __forceinline__ void sgu_phase(const bf16_t* gu, const bf16_t* gv, const float* __restrict__ statsv, const float* __restrict__ lng, const float* __restrict__ lnb, const float* __restrict__ wsp, const float* __restrict__ bs, ...
;     ...
;             const int tf = wid, nks = (16 * tf + 15) / 32 + 1;
;             const int t = 16 * tf + fr; const size_t ro = (size_t)(row0 + t) * GW + g * 128 + 4 * fq; const float bias = bs[g * 128 + t];
;             u32x2 guw[8];
; #pragma unroll
;             for (int cf = 0; cf < 8; ++cf) guw[cf] = *(const u32x2*)(gu + ro + 16 * cf);
;             f32x4 acc[8];
; #pragma unroll
;             for (int cf = 0; cf < 8; ++cf) acc[cf] = (f32x4){0.f, 0.f, 0.f, 0.f};
; #pragma unroll
;             for (int ks = 0; ks < 4; ++ks)
;                 if (ks < nks) {
;                     const bf16x8 Bf = *(const LAS bf16x8*)(Wl + (16 * tf + fr) * P + (32 * ks + 8 * fq) * 2);
; #pragma unroll
;                     for (int cf = 0; cf < 8; ++cf) { const bf16x8 Af = *(const LAS bf16x8*)(vT + (16 * cf + fr) * P + (32 * ks + 8 * fq) * 2); acc[cf] = MFMA16(Af, Bf, acc[cf]); }
;                 }
.LBB0_482:
	s_and_b32 s2, s33, 0xffffff80
	v_add_u32_e32 v58, s2, v126
	v_ashrrev_i32_e32 v59, 31, v58
	v_lshlrev_b64 v[116:117], 10, v[58:59]
	v_or_b32_e32 v58, s79, v116
	v_or_b32_e32 v116, v58, v0
	v_add_u32_e32 v58, s79, v126
	v_ashrrev_i32_e32 v59, 31, v58
	v_readlane_b32 vcc_lo, v251, 43
	v_lshl_add_u64 v[58:59], v[58:59], 2, s[96:97]
	v_readlane_b32 vcc_hi, v251, 44
	global_load_dword v133, v[58:59], off
	v_mov_b32_e32 v90, 0
	v_lshl_add_u64 v[58:59], v[116:117], 1, vcc
	global_load_dwordx2 v[118:119], v[58:59], off
	global_load_dwordx2 v[114:115], v[58:59], off offset:32
	global_load_dwordx2 v[112:113], v[58:59], off offset:64
	global_load_dwordx2 v[110:111], v[58:59], off offset:96
	global_load_dwordx2 v[108:109], v[58:59], off offset:128
	global_load_dwordx2 v[106:107], v[58:59], off offset:160
	global_load_dwordx2 v[104:105], v[58:59], off offset:192
	global_load_dwordx2 v[102:103], v[58:59], off offset:224
	s_andn2_b64 vcc, exec, s[90:91]
	v_mov_b32_e32 v91, 0
	v_mov_b32_e32 v92, 0
	v_mov_b32_e32 v93, 0
	v_mov_b32_e32 v82, 0
	v_mov_b32_e32 v83, v90
	v_mov_b32_e32 v84, v90
	v_mov_b32_e32 v85, v90
	v_mov_b32_e32 v78, v90
	v_mov_b32_e32 v79, v90
	v_mov_b32_e32 v80, v90
	v_mov_b32_e32 v81, v90
	v_mov_b32_e32 v74, v90
	v_mov_b32_e32 v75, v90
	v_mov_b32_e32 v76, v90
	v_mov_b32_e32 v77, v90
	v_mov_b32_e32 v70, v90
	v_mov_b32_e32 v71, v90
	v_mov_b32_e32 v72, v90
	v_mov_b32_e32 v73, v90
	v_mov_b32_e32 v66, v90
	v_mov_b32_e32 v67, v90
	v_mov_b32_e32 v68, v90
	v_mov_b32_e32 v69, v90
	v_mov_b32_e32 v62, v90
	v_mov_b32_e32 v63, v90
	v_mov_b32_e32 v64, v90
	v_mov_b32_e32 v65, v90
	v_mov_b32_e32 v58, v90
	v_mov_b32_e32 v59, v90
	v_mov_b32_e32 v60, v90
	v_mov_b32_e32 v61, v90
	v_mov_b32_e32 v86, v90
	v_mov_b32_e32 v87, v90
	v_mov_b32_e32 v88, v90
	v_mov_b32_e32 v89, v90
	s_cbranch_vccnz .LBB0_486
	ds_read_b128 v[86:89], v131 offset:35840
	ds_read_b128 v[192:195], v132 offset:1024
	ds_read_b128 v[196:199], v132 offset:5376
	ds_read_b128 v[212:215], v132 offset:31488
	ds_read_b128 v[216:219], v132 offset:9728
	ds_read_b128 v[220:223], v132 offset:14080
	ds_read_b128 v[224:227], v132 offset:18432
	ds_read_b128 v[228:231], v132 offset:22784
	ds_read_b128 v[232:235], v132 offset:27136
	s_waitcnt lgkmcnt(7)
	v_mfma_f32_16x16x32_bf16 v[82:85], v[192:195], v[86:89], 0
	s_waitcnt lgkmcnt(6)
	v_mfma_f32_16x16x32_bf16 v[78:81], v[196:199], v[86:89], 0
	s_waitcnt lgkmcnt(5)
	v_mfma_f32_16x16x32_bf16 v[90:93], v[212:215], v[86:89], 0
	s_waitcnt lgkmcnt(4)
	v_mfma_f32_16x16x32_bf16 v[74:77], v[216:219], v[86:89], 0
	s_waitcnt lgkmcnt(3)
	v_mfma_f32_16x16x32_bf16 v[70:73], v[220:223], v[86:89], 0
	s_waitcnt lgkmcnt(2)
	v_mfma_f32_16x16x32_bf16 v[66:69], v[224:227], v[86:89], 0
	s_waitcnt lgkmcnt(1)
	v_mfma_f32_16x16x32_bf16 v[62:65], v[228:231], v[86:89], 0
	s_waitcnt lgkmcnt(0)
	v_mfma_f32_16x16x32_bf16 v[58:61], v[232:235], v[86:89], 0
	v_mov_b32_e32 v86, v90
	v_mov_b32_e32 v87, v91
	v_mov_b32_e32 v88, v92
	v_mov_b32_e32 v89, v93
	s_andn2_b64 vcc, exec, s[86:87]
	s_cbranch_vccz .LBB0_487

; #define LAS __attribute__((address_space(3)))
; #define MFMA16(a, b, c) __builtin_amdgcn_mfma_f32_16x16x32_bf16((a), (b), (c), 0, 0, 0)
; __device__ __forceinline__ void sgu_phase(const bf16_t* gu, const bf16_t* gv, const float* __restrict__ statsv, const float* __restrict__ lng, const float* __restrict__ lnb, const float* __restrict__ wsp, const float* __restrict__ bs, ...
;     ...
;             for (int ks = 0; ks < 4; ++ks)
;                 if (ks < nks) {
;                     const bf16x8 Bf = *(const LAS bf16x8*)(Wl + (16 * tf + fr) * P + (32 * ks + 8 * fq) * 2);
; #pragma unroll
;                     for (int cf = 0; cf < 8; ++cf) { const bf16x8 Af = *(const LAS bf16x8*)(vT + (16 * cf + fr) * P + (32 * ks + 8 * fq) * 2); acc[cf] = MFMA16(Af, Bf, acc[cf]); }
;                 }
.LBB0_485:
	s_nop 0
	ds_read_b128 v[90:93], v131 offset:35968
	ds_read_b128 v[192:195], v132 offset:1152
	ds_read_b128 v[196:199], v132 offset:5504
	ds_read_b128 v[212:215], v132 offset:9856
	ds_read_b128 v[216:219], v132 offset:14208
	ds_read_b128 v[220:223], v132 offset:18560
	ds_read_b128 v[224:227], v132 offset:22912
	ds_read_b128 v[228:231], v132 offset:27264
	ds_read_b128 v[232:235], v132 offset:31616
	s_waitcnt lgkmcnt(7)
	v_mfma_f32_16x16x32_bf16 v[82:85], v[192:195], v[90:93], v[82:85]
	s_waitcnt lgkmcnt(6)
	v_mfma_f32_16x16x32_bf16 v[78:81], v[196:199], v[90:93], v[78:81]
	s_waitcnt lgkmcnt(5)
	v_mfma_f32_16x16x32_bf16 v[74:77], v[212:215], v[90:93], v[74:77]
	s_waitcnt lgkmcnt(4)
	v_mfma_f32_16x16x32_bf16 v[70:73], v[216:219], v[90:93], v[70:73]
	s_waitcnt lgkmcnt(3)
	v_mfma_f32_16x16x32_bf16 v[66:69], v[220:223], v[90:93], v[66:69]
	s_waitcnt lgkmcnt(2)
	v_mfma_f32_16x16x32_bf16 v[62:65], v[224:227], v[90:93], v[62:65]
	s_waitcnt lgkmcnt(1)
	v_mfma_f32_16x16x32_bf16 v[58:61], v[228:231], v[90:93], v[58:61]
	s_waitcnt lgkmcnt(0)
	v_mfma_f32_16x16x32_bf16 v[86:89], v[232:235], v[90:93], v[86:89]
	s_andn2_b64 vcc, exec, s[80:81]
	s_cbranch_vccnz .LBB0_477
	s_branch .LBB0_489

; #define LAS __attribute__((address_space(3)))
; #define MFMA16(a, b, c) __builtin_amdgcn_mfma_f32_16x16x32_bf16((a), (b), (c), 0, 0, 0)
; __device__ __forceinline__ void sgu_phase(const bf16_t* gu, const bf16_t* gv, const float* __restrict__ statsv, const float* __restrict__ lng, const float* __restrict__ lnb, const float* __restrict__ wsp, const float* __restrict__ bs, ...
;     ...
;             for (int ks = 0; ks < 4; ++ks)
;                 if (ks < nks) {
;                     const bf16x8 Bf = *(const LAS bf16x8*)(Wl + (16 * tf + fr) * P + (32 * ks + 8 * fq) * 2);
; #pragma unroll
;                     for (int cf = 0; cf < 8; ++cf) { const bf16x8 Af = *(const LAS bf16x8*)(vT + (16 * cf + fr) * P + (32 * ks + 8 * fq) * 2); acc[cf] = MFMA16(Af, Bf, acc[cf]); }
;                 }
.LBB0_487:
	ds_read_b128 v[134:137], v131 offset:35904
	ds_read_b128 v[192:195], v132 offset:1088
	ds_read_b128 v[196:199], v132 offset:5440
	ds_read_b128 v[212:215], v132 offset:9792
	ds_read_b128 v[216:219], v132 offset:14144
	ds_read_b128 v[220:223], v132 offset:18496
	ds_read_b128 v[224:227], v132 offset:22848
	ds_read_b128 v[228:231], v132 offset:27200
	ds_read_b128 v[232:235], v132 offset:31552
	s_waitcnt lgkmcnt(7)
	v_mfma_f32_16x16x32_bf16 v[82:85], v[192:195], v[134:137], v[82:85]
	s_waitcnt lgkmcnt(6)
	v_mfma_f32_16x16x32_bf16 v[78:81], v[196:199], v[134:137], v[78:81]
	s_waitcnt lgkmcnt(5)
	v_mfma_f32_16x16x32_bf16 v[74:77], v[212:215], v[134:137], v[74:77]
	s_waitcnt lgkmcnt(4)
	v_mfma_f32_16x16x32_bf16 v[70:73], v[216:219], v[134:137], v[70:73]
	s_waitcnt lgkmcnt(3)
	v_mfma_f32_16x16x32_bf16 v[66:69], v[220:223], v[134:137], v[66:69]
	s_waitcnt lgkmcnt(2)
	v_mfma_f32_16x16x32_bf16 v[62:65], v[224:227], v[134:137], v[62:65]
	s_waitcnt lgkmcnt(1)
	v_mfma_f32_16x16x32_bf16 v[58:61], v[228:231], v[134:137], v[58:61]
	s_waitcnt lgkmcnt(0)
	v_mfma_f32_16x16x32_bf16 v[86:89], v[232:235], v[134:137], v[90:93]
	s_andn2_b64 vcc, exec, s[88:89]
	s_cbranch_vccz .LBB0_485

; #define LAS __attribute__((address_space(3)))
; #define MFMA16(a, b, c) __builtin_amdgcn_mfma_f32_16x16x32_bf16((a), (b), (c), 0, 0, 0)
; __device__ __forceinline__ void sgu_phase(const bf16_t* gu, const bf16_t* gv, const float* __restrict__ statsv, const float* __restrict__ lng, const float* __restrict__ lnb, const float* __restrict__ wsp, const float* __restrict__ bs, ...
;     ...
;             for (int ks = 0; ks < 4; ++ks)
;                 if (ks < nks) {
;                     const bf16x8 Bf = *(const LAS bf16x8*)(Wl + (16 * tf + fr) * P + (32 * ks + 8 * fq) * 2);
; #pragma unroll
;                     for (int cf = 0; cf < 8; ++cf) { const bf16x8 Af = *(const LAS bf16x8*)(vT + (16 * cf + fr) * P + (32 * ks + 8 * fq) * 2); acc[cf] = MFMA16(Af, Bf, acc[cf]); }
;                 }
.LBB0_489:
	ds_read_b128 v[90:93], v131 offset:36032
	ds_read_b128 v[192:195], v132 offset:1216
	ds_read_b128 v[196:199], v132 offset:5568
	ds_read_b128 v[212:215], v132 offset:9920
	ds_read_b128 v[216:219], v132 offset:14272
	ds_read_b128 v[220:223], v132 offset:18624
	ds_read_b128 v[224:227], v132 offset:22976
	ds_read_b128 v[228:231], v132 offset:27328
	ds_read_b128 v[232:235], v132 offset:31680
	s_waitcnt lgkmcnt(7)
	v_mfma_f32_16x16x32_bf16 v[82:85], v[192:195], v[90:93], v[82:85]
	s_waitcnt lgkmcnt(6)
	v_mfma_f32_16x16x32_bf16 v[78:81], v[196:199], v[90:93], v[78:81]
	s_waitcnt lgkmcnt(5)
	v_mfma_f32_16x16x32_bf16 v[74:77], v[212:215], v[90:93], v[74:77]
	s_waitcnt lgkmcnt(4)
	v_mfma_f32_16x16x32_bf16 v[70:73], v[216:219], v[90:93], v[70:73]
	s_waitcnt lgkmcnt(3)
	v_mfma_f32_16x16x32_bf16 v[66:69], v[220:223], v[90:93], v[66:69]
	s_waitcnt lgkmcnt(2)
	v_mfma_f32_16x16x32_bf16 v[62:65], v[224:227], v[90:93], v[62:65]
	s_waitcnt lgkmcnt(1)
	v_mfma_f32_16x16x32_bf16 v[58:61], v[228:231], v[90:93], v[58:61]
	s_waitcnt lgkmcnt(0)
	v_mfma_f32_16x16x32_bf16 v[86:89], v[232:235], v[90:93], v[86:89]
	s_branch .LBB0_477
